# differential attention units handed out dynamically from eight per-XCD-group ticket counters (longest first), keeps a head's units on one XCD; on top of flat barrier release
# speedup vs baseline: 1.0079x; 1.0029x over previous
.LBB0_548:
	s_or_b64 exec, exec, s[4:5]
	s_cmpk_gt_i32 s3, 0xff
	s_waitcnt lgkmcnt(0)
	s_barrier
	s_cbranch_scc1 .LBB0_582
	v_mov_b32_e32 v213, 0
	global_load_dword v227, v213, s[52:53]
	v_mbcnt_lo_u32_b32 v0, -1, 0
	s_mov_b32 s5, 0
	s_movk_i32 s44, 0x3000
	v_mov_b64_e32 v[214:215], s[12:13]
	s_mov_b64 s[6:7], 0x1800
	s_movk_i32 s45, 0x1000
	s_movk_i32 s46, 0x110
	s_movk_i32 s47, 0x2000
	s_movk_i32 s48, 0x90
	s_mov_b32 s49, 0xf149f2ca
	s_mov_b32 s50, 0x41000000
	v_mbcnt_hi_u32_b32 v228, -1, v0
	s_mov_b32 s51, 0x800000
	s_movk_i32 s52, 0x4000
	s_mov_b32 s53, 0x8000
	s_mov_b32 s54, 0xc000
	s_mov_b32 s55, 0x10000
	s_mov_b32 s56, 0x14000
	s_mov_b32 s57, 0x18000
	v_mov_b32_e32 v229, 0xf149f2ca
	s_mov_b32 s58, s3
	s_cmpk_lg_u32 s24, 0x100
	s_cbranch_scc1 .Ldf_noremap
	s_mov_b32 s97, s3
	s_and_b32 s99, s3, 7
	s_branch .Ldq_unit
	s_and_b32 s58, s3, 7
	s_lshl_b32 s58, s58, 1
	s_lshr_b32 s96, s3, 7
	s_add_i32 s58, s58, s96
	s_lshl_b32 s58, s58, 4
	s_bfe_u32 s96, s3, 0x40003
	s_or_b32 s58, s58, s96

.Ldq_nw:
	s_barrier
	ds_read_b32 v237, v236
	s_waitcnt lgkmcnt(0)
	v_readfirstlane_b32 s97, v237
	s_nop 3
	s_lshl_b32 s97, s97, 3
	s_add_i32 s97, s97, s99
	s_addk_i32 s97, 0x100
	s_cmpk_gt_i32 s97, 0x3ff
	s_cbranch_scc1 .LBB0_582

.LBB0_553:
	s_or_b32 s4, s63, s60
	v_mov_b32_e32 v233, v225
	s_bitcmp0_b32 s63, 0
	s_cselect_b32 s70, s59, s61
	v_readfirstlane_b32 s68, v233
	s_bfe_u32 s65, s68, 0x20006
	s_lshl_b32 s71, s70, 7
	s_lshl_b32 s67, s65, 5
	v_and_b32_e32 v231, 31, v233
	s_or_b32 s69, s67, s71
	s_add_i32 s40, s4, s62
	v_or_b32_e32 v212, s69, v231
	s_ashr_i32 s41, s40, 31
	s_ashr_i32 s66, s68, 8
	s_lshl_b64 s[42:43], s[40:41], 19
	v_lshl_add_u64 v[0:1], s[38:39], 0, v[212:213]
	s_add_u32 s72, s14, s42
	v_mad_u64_u32 v[2:3], s[40:41], v0, s44, v[214:215]
	s_addc_u32 s73, s15, s43
	v_mad_i32_i24 v3, v1, s44, v3
	s_lshl_b32 s64, s4, 7
	s_lshl_b32 s4, s4, 8
	s_lshl_b32 s40, s66, 6
	v_bfe_u32 v4, v233, 5, 1
	v_lshl_add_u64 v[0:1], v[2:3], 0, s[4:5]
	s_ashr_i32 s41, s40, 31
	v_lshl_add_u64 v[0:1], s[40:41], 1, v[0:1]
	v_lshlrev_b32_e32 v216, 4, v4
	v_mov_b32_e32 v217, v213
	v_lshl_add_u64 v[0:1], v[0:1], 0, v[216:217]
	v_lshl_add_u64 v[2:3], v[0:1], 0, s[6:7]
	v_add_co_u32_e32 v0, vcc, s45, v0
	s_add_u32 s42, s81, s42
	s_nop 0
	v_addc_co_u32_e32 v1, vcc, 0, v1, vcc
	global_load_dwordx4 v[128:131], v[2:3], off offset:32
	global_load_dwordx4 v[132:135], v[2:3], off offset:64
	global_load_dwordx4 v[136:139], v[0:1], off offset:2048
	global_load_dwordx4 v[140:143], v[2:3], off offset:96
	v_lshlrev_b32_e32 v0, 3, v233
	s_addc_u32 s43, s82, s43
	v_ashrrev_i32_e32 v1, 31, v0
	s_lshl_b32 s41, s70, 1
	v_lshlrev_b64 v[0:1], 1, v[0:1]
	v_mov_b32_e32 v246, v0
	v_add_u32_e32 v245, 0x2000, v0
	s_or_b32 s70, s41, 1
	s_mov_b64 s[88:89], s[72:73]
	v_lshl_add_u64 v[218:219], s[72:73], 0, v[0:1]
	s_lshl_b32 s4, s70, 14
	s_mov_b64 s[90:91], s[42:43]
	v_lshl_add_u64 v[220:221], s[42:43], 0, v[0:1]
	v_lshl_add_u64 v[0:1], v[218:219], 0, s[4:5]
	s_barrier
	v_lshl_add_u64 v[2:3], v[220:221], 0, s[4:5]
	global_load_dwordx4 v[144:147], v[0:1], off
	global_load_dwordx4 v[148:151], v[2:3], off
	v_add_co_u32_e32 v0, vcc, s47, v0
	v_lshlrev_b32_e32 v217, 3, v4
	s_nop 0
	v_addc_co_u32_e32 v1, vcc, 0, v1, vcc
	v_add_co_u32_e32 v2, vcc, s47, v2
	v_mul_u32_u24_e32 v230, 0x110, v231
	s_nop 0
	v_addc_co_u32_e32 v3, vcc, 0, v3, vcc
	global_load_dwordx4 v[152:155], v[0:1], off
	global_load_dwordx4 v[156:159], v[2:3], off
	v_lshrrev_b32_e32 v0, 4, v233
	v_lshlrev_b32_e32 v2, 4, v233
	v_mov_b32_e32 v1, 0x14e60
	v_lshrrev_b32_e32 v3, 3, v233
	v_mul_lo_u32 v5, v0, s46
	v_and_b32_e32 v0, 0x70, v2
	v_and_b32_e32 v6, 0xf0, v2
	v_mad_u64_u32 v[222:223], s[42:43], v3, s48, v[0:1]
	v_add3_u32 v234, 0, v5, v6
	v_add_u32_e32 v0, 0, v222
	v_or_b32_e32 v2, s40, v217
	v_lshlrev_b32_e32 v2, 1, v2
	v_mov_b32_e32 v48, v213
	v_mov_b32_e32 v49, v213
	v_mov_b32_e32 v62, v213
	v_mov_b32_e32 v63, v213
	v_lshlrev_b32_e32 v232, 2, v4
	v_add3_u32 v235, 0, v230, v2
	v_mad_u32_u24 v236, v231, s48, v1
	v_mov_b32_e32 v50, v213
	v_mov_b32_e32 v51, v213
	v_mov_b32_e32 v52, v213
	v_mov_b32_e32 v53, v213
	v_mov_b32_e32 v54, v213
	v_mov_b32_e32 v55, v213
	v_mov_b32_e32 v56, v213
	v_mov_b32_e32 v57, v213
	v_mov_b32_e32 v58, v213
	v_mov_b32_e32 v59, v213
	v_mov_b32_e32 v60, v213
	v_mov_b32_e32 v61, v213
	v_mov_b64_e32 v[32:33], v[48:49]
	v_mov_b64_e32 v[16:17], v[48:49]
	s_waitcnt vmcnt(8)
	v_mov_b64_e32 v[78:79], v[62:63]
	s_mov_b32 s72, 1
	s_waitcnt vmcnt(3)
	ds_write_b128 v234, v[144:147]
	s_waitcnt vmcnt(2)
	ds_write_b128 v0, v[148:151] offset:34816
	s_waitcnt vmcnt(1)
	ds_write_b128 v234, v[152:155] offset:8704
	s_waitcnt vmcnt(0)
	ds_write_b128 v0, v[156:159] offset:44032
	v_mov_b32_e32 v0, 0x14e40
	v_mad_u32_u24 v237, v231, s48, v0
	v_mov_b32_e32 v0, 0x14e20
	v_mad_u32_u24 v238, v231, s48, v0
	v_mov_b32_e32 v0, 0x14e00
	v_mad_u32_u24 v239, v231, s48, v0
	v_mov_b32_e32 v0, 0x13c00
	v_mad_u32_u24 v240, v231, s48, v0
	v_mov_b32_e32 v0, 0x12a60
	v_mad_u32_u24 v241, v231, s48, v0
	v_mov_b32_e32 v0, 0x12a40
	v_mad_u32_u24 v242, v231, s48, v0
	v_mov_b32_e32 v0, 0x12a20
	v_mad_u32_u24 v243, v231, s48, v0
	v_mov_b32_e32 v0, 0x12a00
	v_mad_u32_u24 v244, v231, s48, v0
	v_mov_b32_e32 v0, 0x11800
	v_mad_u32_u24 v248, v231, s48, v0
	v_add_u32_e32 v248, v248, v216
	v_mov_b64_e32 v[0:1], v[48:49]
	s_mov_b32 s73, 0
	s_mov_b32 s74, 2
	s_or_b32 s75, s69, 31
	s_mov_b64 s[42:43], 0
	v_mov_b32_e32 v224, 1.0
	v_mov_b32_e32 v249, 0xf149f2ca
	v_mov_b32_e32 v223, 0
	s_mov_b32 s4, s41
	v_mov_b64_e32 v[34:35], v[50:51]
	v_mov_b64_e32 v[36:37], v[52:53]
	v_mov_b64_e32 v[38:39], v[54:55]
	v_mov_b64_e32 v[40:41], v[56:57]
	v_mov_b64_e32 v[42:43], v[58:59]
	v_mov_b64_e32 v[44:45], v[60:61]
	v_mov_b64_e32 v[46:47], v[62:63]
	v_mov_b64_e32 v[18:19], v[50:51]
	v_mov_b64_e32 v[20:21], v[52:53]
	v_mov_b64_e32 v[22:23], v[54:55]
	v_mov_b64_e32 v[24:25], v[56:57]
	v_mov_b64_e32 v[26:27], v[58:59]
	v_mov_b64_e32 v[28:29], v[60:61]
	v_mov_b64_e32 v[30:31], v[62:63]
	v_mov_b64_e32 v[2:3], v[50:51]
	v_mov_b64_e32 v[4:5], v[52:53]
	v_mov_b64_e32 v[6:7], v[54:55]
	v_mov_b64_e32 v[8:9], v[56:57]
	v_mov_b64_e32 v[10:11], v[58:59]
	v_mov_b64_e32 v[12:13], v[60:61]
	v_mov_b64_e32 v[14:15], v[62:63]
	v_mov_b64_e32 v[76:77], v[60:61]
	v_mov_b64_e32 v[74:75], v[58:59]
	v_mov_b64_e32 v[72:73], v[56:57]
	v_mov_b64_e32 v[70:71], v[54:55]
	v_mov_b64_e32 v[68:69], v[52:53]
	v_mov_b64_e32 v[66:67], v[50:51]
	v_mov_b64_e32 v[64:65], v[48:49]
	s_cmpk_lg_u32 s24, 0x100
	s_cbranch_scc1 .Ldq_noat
	s_cmp_ge_u32 s68, 64
	s_cbranch_scc1 .Ldq_noat
	s_lshl_b32 s94, s99, 6
	s_add_u32 s94, s94, 0x83600
	s_add_u32 s94, s22, s94
	s_addc_u32 s95, s23, 0
	s_mov_b64 s[92:93], exec
	s_mov_b64 exec, 1
	v_mov_b32_e32 v237, 0
	v_mov_b32_e32 v238, 1
	global_atomic_add v250, v237, v238, s[94:95] sc0
	s_mov_b64 exec, s[92:93]
.Ldq_noat:
	s_waitcnt lgkmcnt(0)
	s_barrier
	s_branch .LBB0_555
	s_nop 0
	s_nop 0
	s_nop 0
	s_nop 0
	s_nop 0
	s_nop 0
	s_nop 0
	s_nop 0
	s_nop 0
	s_nop 0
	s_nop 0

.LBB0_585:
	s_and_b32 s4, s63, 7
	s_lshl_b32 s5, s4, 2
	v_mov_b32_e32 v6, v225
	s_or_b32 s71, s5, 2
	s_and_b32 s42, s3, 7
	v_readfirstlane_b32 s5, v6
	s_ashr_i32 s64, s5, 6
	s_lshl_b32 s65, s4, 8
	s_ashr_i32 s4, s3, 6
	s_lshl_b32 s5, s42, 8
	s_lshl_b32 s66, s64, 5
	s_add_i32 s66, s66, s5
	s_ashr_i32 s5, s4, 31
	s_bfe_u32 s8, s3, 0x30003
	v_and_b32_e32 v7, 31, v6
	s_lshl_b64 s[38:39], s[4:5], 11
	s_lshl_b32 s4, s4, 3
	s_waitcnt vmcnt(2)
	v_or_b32_e32 v150, s66, v7
	s_or_b32 s4, s4, s8
	s_ashr_i32 s5, s4, 31
	v_ashrrev_i32_e32 v151, 31, v150
	s_lshl_b64 s[4:5], s[4:5], 19
	v_lshl_add_u64 v[2:3], s[38:39], 0, v[150:151]
	s_add_u32 s6, s14, s4
	v_mad_u64_u32 v[4:5], s[40:41], v2, s44, v[146:147]
	v_bfe_u32 v8, v6, 5, 1
	s_addc_u32 s7, s15, s5
	v_mad_i32_i24 v5, v3, s44, v5
	s_lshl_b32 s67, s8, 7
	s_lshl_b32 s8, s8, 8
	v_lshl_add_u64 v[2:3], v[4:5], 0, s[8:9]
	v_lshlrev_b32_e32 v0, 4, v8
	v_lshl_add_u64 v[2:3], v[2:3], 0, v[0:1]
	global_load_dwordx4 v[98:101], v[2:3], off
	global_load_dwordx4 v[102:105], v[2:3], off offset:32
	global_load_dwordx4 v[106:109], v[2:3], off offset:64
	global_load_dwordx4 v[110:113], v[2:3], off offset:96
	global_load_dwordx4 v[114:117], v[2:3], off offset:128
	global_load_dwordx4 v[118:121], v[2:3], off offset:160
	global_load_dwordx4 v[122:125], v[2:3], off offset:192
	global_load_dwordx4 v[126:129], v[2:3], off offset:224
	v_lshlrev_b32_e32 v2, 3, v6
	s_add_u32 s4, s81, s4
	v_ashrrev_i32_e32 v3, 31, v2
	s_addc_u32 s5, s82, s5
	v_lshlrev_b64 v[2:3], 1, v[2:3]
	v_mov_b32_e32 v228, v2
	v_add_u32_e32 v229, 0x2000, v2
	s_waitcnt vmcnt(9)
	s_mov_b64 s[90:91], s[4:5]
	v_lshl_add_u64 v[154:155], s[4:5], 0, v[2:3]
	s_lshl_b32 s4, s42, 16
	s_mov_b64 s[88:89], s[6:7]
	v_lshl_add_u64 v[152:153], s[6:7], 0, v[2:3]
	s_or_b32 s8, s4, 0xc000
	v_lshl_add_u64 v[2:3], v[152:153], 0, s[8:9]
	s_barrier
	v_lshl_add_u64 v[4:5], v[154:155], 0, s[8:9]
	global_load_dwordx4 v[130:133], v[2:3], off
	global_load_dwordx4 v[134:137], v[4:5], off
	v_add_co_u32_e32 v2, vcc, s46, v2
	v_and_b32_e32 v149, 63, v6
	s_nop 0
	v_addc_co_u32_e32 v3, vcc, 0, v3, vcc
	v_add_co_u32_e32 v4, vcc, s46, v4
	v_mul_u32_u24_e32 v197, 0x110, v7
	s_nop 0
	v_addc_co_u32_e32 v5, vcc, 0, v5, vcc
	global_load_dwordx4 v[138:141], v[2:3], off
	global_load_dwordx4 v[142:145], v[4:5], off
	v_lshlrev_b32_e32 v2, 4, v6
	v_lshrrev_b32_e32 v3, 3, v6
	v_lshrrev_b32_e32 v4, 4, v6
	v_and_b32_e32 v148, 0xf0, v2
	v_and_b32_e32 v2, 0x70, v2
	s_waitcnt vmcnt(12)
	v_mad_u64_u32 v[156:157], s[4:5], v4, s47, v[148:149]
	v_mad_u64_u32 v[158:159], s[4:5], v3, s48, v[2:3]
	v_lshlrev_b32_e32 v5, 7, v7
	v_add3_u32 v157, 0, v197, v0
	v_add_u32_e32 v0, 0, v156
	v_add_u32_e32 v2, 0, v158
	v_mov_b32_e32 v14, v1
	v_mov_b32_e32 v15, v1
	v_lshlrev_b32_e32 v151, 3, v8
	s_lshl_b32 s4, s64, 2
	v_lshlrev_b32_e32 v159, 2, v8
	v_sub_u32_e32 v198, v157, v5
	v_mov_b32_e32 v3, v1
	v_mov_b32_e32 v4, v1
	v_mov_b32_e32 v5, v1
	v_mov_b32_e32 v6, v1
	v_mov_b32_e32 v7, v1
	v_mov_b32_e32 v8, v1
	v_mov_b32_e32 v9, v1
	v_mov_b32_e32 v10, v1
	v_mov_b32_e32 v11, v1
	v_mov_b32_e32 v12, v1
	v_mov_b32_e32 v13, v1
	s_add_i32 s69, s4, 0
	v_cmp_eq_u32_e64 s[6:7], 0, v149
	s_or_b32 s68, s66, 30
	s_add_i32 s69, s69, 0x11800
	v_cmp_gt_u32_e64 s[4:5], 32, v149
	s_mov_b64 s[42:43], 0
	s_mov_b32 s70, s9
	s_mov_b32 s8, s71
	s_mov_b32 s71, s9
	s_waitcnt vmcnt(3)
	ds_write_b128 v0, v[130:133]
	s_waitcnt vmcnt(2)
	ds_write_b128 v2, v[134:137] offset:17408
	s_waitcnt vmcnt(1)
	ds_write_b128 v0, v[138:141] offset:8704
	s_waitcnt vmcnt(0)
	ds_write_b128 v2, v[142:145] offset:26624
	v_mov_b32_e32 v0, v1
	v_mov_b32_e32 v2, v1
	v_mov_b64_e32 v[64:65], v[14:15]
	v_mov_b64_e32 v[48:49], v[14:15]
	v_mov_b64_e32 v[32:33], v[14:15]
	v_mov_b64_e32 v[62:63], v[12:13]
	v_mov_b64_e32 v[60:61], v[10:11]
	v_mov_b64_e32 v[58:59], v[8:9]
	v_mov_b64_e32 v[56:57], v[6:7]
	v_mov_b64_e32 v[54:55], v[4:5]
	v_mov_b64_e32 v[52:53], v[2:3]
	v_mov_b64_e32 v[50:51], v[0:1]
	v_mov_b64_e32 v[46:47], v[12:13]
	v_mov_b64_e32 v[44:45], v[10:11]
	v_mov_b64_e32 v[42:43], v[8:9]
	v_mov_b64_e32 v[40:41], v[6:7]
	v_mov_b64_e32 v[38:39], v[4:5]
	v_mov_b64_e32 v[36:37], v[2:3]
	v_mov_b64_e32 v[34:35], v[0:1]
	v_mov_b64_e32 v[30:31], v[12:13]
	v_mov_b64_e32 v[28:29], v[10:11]
	v_mov_b64_e32 v[26:27], v[8:9]
	v_mov_b64_e32 v[24:25], v[6:7]
	v_mov_b64_e32 v[22:23], v[4:5]
	v_mov_b64_e32 v[20:21], v[2:3]
	v_mov_b64_e32 v[18:19], v[0:1]
	v_mov_b64_e32 v[16:17], v[14:15]
	v_mov_b64_e32 v[14:15], v[12:13]
	v_mov_b64_e32 v[12:13], v[10:11]
	v_mov_b64_e32 v[10:11], v[8:9]
	v_mov_b64_e32 v[8:9], v[6:7]
	v_mov_b64_e32 v[6:7], v[4:5]
	v_mov_b64_e32 v[4:5], v[2:3]
	v_mov_b64_e32 v[2:3], v[0:1]
	v_mov_b32_e32 v0, 0
	s_waitcnt lgkmcnt(0)
	s_barrier
	s_branch .LBB0_587
	s_nop 0
	s_nop 0
	s_nop 0
	s_nop 0
	s_nop 0
	s_nop 0
	s_nop 0
	s_nop 0
	s_nop 0
	s_nop 0
	s_nop 0
	s_nop 0
	s_nop 0
	s_nop 0
	s_nop 0
	s_nop 0
	s_nop 0
	s_nop 0
	s_nop 0
	s_nop 0
	s_nop 0
	s_nop 0
	s_nop 0
	s_nop 0
	s_nop 0
